# attention loop: exposed ds_bpermute butterflies -> DPP row ops / permlane16+32 swaps (20 sites), bias blocks via v_cndmask instead of exec masking
# speedup vs baseline: 1.0048x; 1.0046x over previous
.LBB0_322:
	s_waitcnt vmcnt(3)
	v_and_b32_e32 v65, 0xffff0000, v40
	v_lshlrev_b32_e32 v64, 16, v40
	v_mul_f32_e32 v58, v65, v65
	v_lshlrev_b32_e32 v66, 16, v41
	v_fmac_f32_e32 v58, v64, v64
	v_and_b32_e32 v67, 0xffff0000, v41
	v_fmac_f32_e32 v58, v66, v66
	v_lshlrev_b32_e32 v72, 16, v42
	v_fmac_f32_e32 v58, v67, v67
	v_and_b32_e32 v73, 0xffff0000, v42
	v_fmac_f32_e32 v58, v72, v72
	v_lshlrev_b32_e32 v74, 16, v43
	v_fmac_f32_e32 v58, v73, v73
	v_and_b32_e32 v75, 0xffff0000, v43
	v_fmac_f32_e32 v58, v74, v74
	v_fmac_f32_e32 v58, v75, v75
	s_waitcnt vmcnt(2)
	v_lshlrev_b32_e32 v80, 16, v44
	v_and_b32_e32 v81, 0xffff0000, v44
	v_fmac_f32_e32 v58, v80, v80
	v_lshlrev_b32_e32 v82, 16, v45
	v_fmac_f32_e32 v58, v81, v81
	v_and_b32_e32 v83, 0xffff0000, v45
	v_fmac_f32_e32 v58, v82, v82
	v_lshlrev_b32_e32 v84, 16, v46
	v_fmac_f32_e32 v58, v83, v83
	v_and_b32_e32 v85, 0xffff0000, v46
	v_fmac_f32_e32 v58, v84, v84
	v_lshlrev_b32_e32 v86, 16, v47
	v_fmac_f32_e32 v58, v85, v85
	v_and_b32_e32 v87, 0xffff0000, v47
	v_fmac_f32_e32 v58, v86, v86
	v_fmac_f32_e32 v58, v87, v87
	s_waitcnt vmcnt(1)
	v_lshlrev_b32_e32 v88, 16, v48
	v_and_b32_e32 v89, 0xffff0000, v48
	v_fmac_f32_e32 v58, v88, v88
	v_lshlrev_b32_e32 v90, 16, v49
	v_fmac_f32_e32 v58, v89, v89
	v_and_b32_e32 v91, 0xffff0000, v49
	v_fmac_f32_e32 v58, v90, v90
	v_lshlrev_b32_e32 v92, 16, v50
	v_fmac_f32_e32 v58, v91, v91
	v_and_b32_e32 v93, 0xffff0000, v50
	v_fmac_f32_e32 v58, v92, v92
	v_lshlrev_b32_e32 v94, 16, v51
	v_fmac_f32_e32 v58, v93, v93
	v_and_b32_e32 v95, 0xffff0000, v51
	v_fmac_f32_e32 v58, v94, v94
	s_waitcnt vmcnt(0)
	v_and_b32_e32 v68, 0xffff0000, v52
	v_lshlrev_b32_e32 v69, 16, v52
	v_fmac_f32_e32 v58, v95, v95
	v_pk_mul_f32 v[56:57], v[68:69], v[68:69]
	v_and_b32_e32 v70, 0xffff0000, v53
	v_add_f32_e32 v57, v57, v58
	v_lshlrev_b32_e32 v71, 16, v53
	v_add_f32_e32 v58, v56, v57
	v_pk_mul_f32 v[56:57], v[70:71], v[70:71]
	v_and_b32_e32 v76, 0xffff0000, v54
	v_add_f32_e32 v57, v57, v58
	v_lshlrev_b32_e32 v77, 16, v54
	v_add_f32_e32 v58, v56, v57
	v_pk_mul_f32 v[56:57], v[76:77], v[76:77]
	v_and_b32_e32 v78, 0xffff0000, v55
	v_add_f32_e32 v57, v57, v58
	v_lshlrev_b32_e32 v79, 16, v55
	v_add_f32_e32 v58, v56, v57
	v_pk_mul_f32 v[56:57], v[78:79], v[78:79]
	s_mov_b32 s0, 0x800000
	v_add_f32_e32 v57, v57, v58
	v_add_f32_e32 v56, v56, v57
	v_mov_b32_e32 v57, v56
	s_cmp_lg_u32 s38, 0x18000
	s_cselect_b64 s[14:15], -1, 0
	s_cmp_eq_u32 s38, 0x18000
	s_waitcnt lgkmcnt(0)
	s_nop 1
	v_permlane16_swap_b32_e32 v57, v56
	v_add_f32_e32 v56, v56, v57
	v_mov_b32_e32 v57, v56
	s_waitcnt lgkmcnt(0)
	s_nop 1
	v_permlane32_swap_b32_e32 v57, v56
	v_add_f32_e32 v56, v56, v57
	v_fmamk_f32 v56, v56, 0x3c000000, v194
	v_cmp_gt_f32_e32 vcc, s0, v56
	v_mul_f32_e32 v57, 0x4b800000, v56
	s_nop 0
	v_cndmask_b32_e32 v56, v56, v57, vcc
	v_rsq_f32_e32 v56, v56
	s_nop 0
	v_mul_f32_e32 v57, 0x45800000, v56
	v_cndmask_b32_e32 v56, v56, v57, vcc
	v_mul_f32_e32 v96, 0x3e0293ee, v56
	ds_read_b128 v[56:59], v211
	ds_read_b128 v[60:63], v211 offset:16
	s_waitcnt lgkmcnt(1)
	v_mul_f32_e32 v56, v56, v96
	s_waitcnt lgkmcnt(0)
	v_mul_f32_e32 v60, v60, v96
	v_mul_f32_e32 v57, v57, v96
	v_mul_f32_e32 v61, v61, v96
	v_mul_f32_e32 v58, v58, v96
	v_mul_f32_e32 v62, v62, v96
	v_mul_f32_e32 v59, v59, v96
	v_mul_f32_e32 v63, v63, v96
	v_mul_f32_e32 v56, v56, v64
	v_mul_f32_e32 v60, v60, v72
	v_mul_f32_e32 v57, v57, v65
	v_mul_f32_e32 v61, v61, v73
	v_mul_f32_e32 v58, v58, v66
	v_mul_f32_e32 v62, v62, v74
	v_mul_f32_e32 v59, v59, v67
	v_mul_f32_e32 v63, v63, v75
	v_cvt_pk_bf16_f32 v56, v56, v57
	v_cvt_pk_bf16_f32 v57, v58, v59
	v_cvt_pk_bf16_f32 v58, v60, v61
	v_cvt_pk_bf16_f32 v59, v62, v63
	ds_read_b128 v[60:63], v211 offset:128
	ds_read_b128 v[64:67], v211 offset:144
	s_waitcnt lgkmcnt(1)
	v_mul_f32_e32 v60, v60, v96
	s_waitcnt lgkmcnt(0)
	v_mul_f32_e32 v64, v64, v96
	v_mul_f32_e32 v61, v61, v96
	v_mul_f32_e32 v65, v65, v96
	v_mul_f32_e32 v62, v62, v96
	v_mul_f32_e32 v66, v66, v96
	v_mul_f32_e32 v63, v63, v96
	v_mul_f32_e32 v67, v67, v96
	v_mul_f32_e32 v60, v60, v80
	v_mul_f32_e32 v64, v64, v84
	v_mul_f32_e32 v61, v61, v81
	v_mul_f32_e32 v65, v65, v85
	v_mul_f32_e32 v62, v62, v82
	v_mul_f32_e32 v66, v66, v86
	v_mul_f32_e32 v63, v63, v83
	v_mul_f32_e32 v67, v67, v87
	v_cvt_pk_bf16_f32 v72, v60, v61
	v_cvt_pk_bf16_f32 v73, v62, v63
	v_cvt_pk_bf16_f32 v74, v64, v65
	v_cvt_pk_bf16_f32 v75, v66, v67
	ds_read_b128 v[60:63], v211 offset:256
	ds_read_b128 v[64:67], v211 offset:272
	s_waitcnt lgkmcnt(1)
	v_mul_f32_e32 v60, v60, v96
	s_waitcnt lgkmcnt(0)
	v_mul_f32_e32 v64, v64, v96
	v_mul_f32_e32 v61, v61, v96
	v_mul_f32_e32 v65, v65, v96
	v_mul_f32_e32 v62, v62, v96
	v_mul_f32_e32 v66, v66, v96
	v_mul_f32_e32 v63, v63, v96
	v_mul_f32_e32 v67, v67, v96
	v_mul_f32_e32 v60, v60, v88
	v_mul_f32_e32 v64, v64, v92
	v_mul_f32_e32 v61, v61, v89
	v_mul_f32_e32 v65, v65, v93
	v_mul_f32_e32 v62, v62, v90
	v_mul_f32_e32 v66, v66, v94
	v_mul_f32_e32 v63, v63, v91
	v_mul_f32_e32 v67, v67, v95
	v_cvt_pk_bf16_f32 v80, v60, v61
	v_cvt_pk_bf16_f32 v81, v62, v63
	v_cvt_pk_bf16_f32 v82, v64, v65
	v_cvt_pk_bf16_f32 v83, v66, v67
	ds_read_b128 v[60:63], v211 offset:384
	ds_read_b128 v[64:67], v211 offset:400
	s_waitcnt lgkmcnt(1)
	v_mul_f32_e32 v60, v60, v96
	s_waitcnt lgkmcnt(0)
	v_mul_f32_e32 v64, v64, v96
	v_mul_f32_e32 v61, v61, v96
	v_mul_f32_e32 v65, v65, v96
	v_mul_f32_e32 v62, v62, v96
	v_mul_f32_e32 v66, v66, v96
	v_mul_f32_e32 v63, v63, v96
	v_mul_f32_e32 v67, v67, v96
	v_mul_f32_e32 v60, v60, v69
	v_mul_f32_e32 v64, v64, v77
	v_mul_f32_e32 v61, v61, v68
	v_mul_f32_e32 v65, v65, v76
	v_mul_f32_e32 v62, v62, v71
	v_mul_f32_e32 v66, v66, v79
	v_mul_f32_e32 v63, v63, v70
	v_mul_f32_e32 v67, v67, v78
	v_cvt_pk_bf16_f32 v84, v60, v61
	v_cvt_pk_bf16_f32 v85, v62, v63
	v_cvt_pk_bf16_f32 v86, v64, v65
	v_cvt_pk_bf16_f32 v87, v66, v67
	s_cbranch_scc1 .LBB0_324
	s_and_b32 s0, s37, s36
	s_lshl_b32 s39, s0, 7
	v_add_u32_e32 v0, s39, v137
	s_lshr_b32 s1, s37, s35
	v_ashrrev_i32_e32 v1, 31, v0
	v_lshlrev_b64 v[0:1], s34, v[0:1]
	s_or_b32 s0, s2, s1
	s_mov_b32 s1, s3
	v_lshl_add_u64 v[0:1], v[0:1], 0, s[0:1]
	s_mov_b32 s41, 0x9000
	v_mad_u64_u32 v[2:3], s[10:11], v0, s41, v[120:121]
	v_mul_lo_u32 v4, v1, s41
	s_movk_i32 s40, 0x1000
	v_add_u32_e32 v1, v4, v3
	v_add_co_u32_e32 v2, vcc, s40, v2
	s_nop 1
	v_addc_co_u32_e32 v3, vcc, 0, v1, vcc
	v_mad_u64_u32 v[0:1], s[10:11], v0, s41, v[122:123]
	v_add_u32_e32 v1, v4, v1
	v_add_u32_e32 v4, s39, v140
	v_ashrrev_i32_e32 v5, 31, v4
	v_lshlrev_b64 v[4:5], s34, v[4:5]
	v_lshl_add_u64 v[4:5], v[4:5], 0, s[0:1]
	v_mad_u64_u32 v[6:7], s[10:11], v4, s41, v[120:121]
	v_mul_lo_u32 v5, v5, s41
	v_add_u32_e32 v7, v5, v7
	v_add_co_u32_e32 v6, vcc, s40, v6
	s_nop 1
	v_addc_co_u32_e32 v7, vcc, 0, v7, vcc
	global_load_dwordx4 v[24:27], v[2:3], off
	global_load_dwordx4 v[28:31], v[6:7], off
	v_mad_u64_u32 v[2:3], s[10:11], v4, s41, v[122:123]
	v_add_u32_e32 v4, s39, v141
	v_add_u32_e32 v3, v5, v3
	v_ashrrev_i32_e32 v5, 31, v4
	v_lshlrev_b64 v[4:5], s34, v[4:5]
	v_lshl_add_u64 v[4:5], v[4:5], 0, s[0:1]
	v_mad_u64_u32 v[6:7], s[10:11], v4, s41, v[120:121]
	v_mul_lo_u32 v8, v5, s41
	v_add_u32_e32 v5, v8, v7
	v_add_co_u32_e32 v6, vcc, s40, v6
	s_nop 1
	v_addc_co_u32_e32 v7, vcc, 0, v5, vcc
	v_mad_u64_u32 v[4:5], s[10:11], v4, s41, v[122:123]
	v_add_u32_e32 v5, v8, v5
	v_add_u32_e32 v8, s39, v142
	v_ashrrev_i32_e32 v9, 31, v8
	v_lshlrev_b64 v[8:9], s34, v[8:9]
	v_lshl_add_u64 v[8:9], v[8:9], 0, s[0:1]
	v_mad_u64_u32 v[10:11], s[10:11], v8, s41, v[120:121]
	v_mul_lo_u32 v9, v9, s41
	v_add_u32_e32 v11, v9, v11
	v_add_co_u32_e32 v10, vcc, s40, v10
	s_nop 1
	v_addc_co_u32_e32 v11, vcc, 0, v11, vcc
	global_load_dwordx4 v[32:35], v[6:7], off
	global_load_dwordx4 v[36:39], v[10:11], off
	v_mad_u64_u32 v[6:7], s[10:11], v8, s41, v[122:123]
	v_add_u32_e32 v7, v9, v7
	global_load_dwordx2 v[112:113], v[0:1], off
	global_load_dwordx2 v[114:115], v[2:3], off
	global_load_dwordx2 v[116:117], v[4:5], off
	global_load_dwordx2 v[118:119], v[6:7], off
	v_add_u32_e32 v0, s39, v145
	v_ashrrev_i32_e32 v1, 31, v0
	v_lshlrev_b64 v[0:1], s34, v[0:1]
	v_lshl_add_u64 v[0:1], v[0:1], 0, s[0:1]
	v_mad_u64_u32 v[12:13], s[0:1], v0, s41, v[124:125]
	v_mov_b32_e32 v0, v13
	v_mad_u64_u32 v[0:1], s[0:1], v1, s41, v[0:1]
	v_mov_b32_e32 v13, v0
	global_load_dwordx4 v[0:3], v[12:13], off
	global_load_dwordx4 v[4:7], v[12:13], off offset:64
	global_load_dwordx4 v[8:11], v[12:13], off offset:128
	s_nop 0
	global_load_dwordx4 v[12:15], v[12:13], off offset:192
.LBB0_324:
	s_add_i32 vcc_lo, s37, -1
	s_and_b32 s39, vcc_lo, s36
	s_not_b32 s0, s39
	s_add_i32 s1, s33, s0
	s_lshl_b32 s1, s1, 7
	s_and_b32 s1, s1, 0x80
	v_or_b32_e32 v60, s1, v187
	v_readlane_b32 s1, v255, 19
	s_add_i32 s1, s1, s0
	s_lshl_b32 s1, s1, 7
	s_and_b32 s1, s1, 0x80
	v_or_b32_e32 v88, s1, v188
	v_lshl_add_u32 v68, v60, 8, 0
	v_lshl_add_u32 v96, v88, 8, 0
	v_add_u32_e32 v60, v68, v147
	v_add_u32_e32 v64, v68, v148
	v_add_u32_e32 v69, v68, v149
	v_add_u32_e32 v76, v68, v150
	v_add_u32_e32 v88, v96, v147
	v_add_u32_e32 v92, v96, v148
	v_add_u32_e32 v97, v96, v149
	ds_read_b128 v[60:63], v60
	ds_read_b128 v[64:67], v64
	ds_read_b128 v[68:71], v69
	ds_read_b128 v[76:79], v76
	ds_read_b128 v[88:91], v88
	ds_read_b128 v[92:95], v92
	v_add_u32_e32 v100, v96, v150
	ds_read_b128 v[96:99], v97
	ds_read_b128 v[220:223], v100
	s_waitcnt lgkmcnt(7)
	v_mfma_f32_16x16x32_bf16 v[60:63], v[60:63], v[56:59], 0
	s_waitcnt lgkmcnt(6)
	v_mfma_f32_16x16x32_bf16 v[60:63], v[64:67], v[72:75], v[60:63]
	s_waitcnt lgkmcnt(5)
	v_mfma_f32_16x16x32_bf16 v[60:63], v[68:71], v[80:83], v[60:63]
	s_waitcnt lgkmcnt(4)
	v_mfma_f32_16x16x32_bf16 v[100:103], v[76:79], v[84:87], v[60:63]
	s_add_i32 s1, s17, s0
	s_lshl_b32 s1, s1, 7
	s_and_b32 s1, s1, 0x80
	s_nop 2
	v_or_b32_e32 v60, s1, v189
	v_lshl_add_u32 v68, v60, 8, 0
	v_add_u32_e32 v60, v68, v147
	v_add_u32_e32 v64, v68, v148
	v_add_u32_e32 v69, v68, v149
	v_add_u32_e32 v76, v68, v150
	ds_read_b128 v[60:63], v60
	ds_read_b128 v[64:67], v64
	ds_read_b128 v[68:71], v69
	ds_read_b128 v[76:79], v76
	s_waitcnt lgkmcnt(7)
	v_mfma_f32_16x16x32_bf16 v[88:91], v[88:91], v[56:59], 0
	s_waitcnt lgkmcnt(6)
	v_mfma_f32_16x16x32_bf16 v[88:91], v[92:95], v[72:75], v[88:91]
	s_waitcnt lgkmcnt(5)
	v_mfma_f32_16x16x32_bf16 v[88:91], v[96:99], v[80:83], v[88:91]
	s_waitcnt lgkmcnt(4)
	v_mfma_f32_16x16x32_bf16 v[96:99], v[220:223], v[84:87], v[88:91]
	v_readlane_b32 s1, v255, 21
	s_add_i32 s1, s1, s0
	s_lshl_b32 s1, s1, 7
	s_and_b32 s1, s1, 0x80
	s_nop 1
	v_or_b32_e32 v88, s1, v190
	v_lshl_add_u32 v92, v88, 8, 0
	v_add_u32_e32 v88, v92, v147
	v_add_u32_e32 v93, v92, v148
	ds_read_b128 v[88:91], v88
	ds_read_b128 v[220:223], v93
	v_add_u32_e32 v93, v92, v149
	v_add_u32_e32 v92, v92, v150
	ds_read_b128 v[224:227], v93
	ds_read_b128 v[228:231], v92
	s_waitcnt lgkmcnt(7)
	v_mfma_f32_16x16x32_bf16 v[60:63], v[60:63], v[56:59], 0
	s_waitcnt lgkmcnt(6)
	v_mfma_f32_16x16x32_bf16 v[60:63], v[64:67], v[72:75], v[60:63]
	s_waitcnt lgkmcnt(5)
	v_mfma_f32_16x16x32_bf16 v[60:63], v[68:71], v[80:83], v[60:63]
	s_waitcnt lgkmcnt(4)
	v_mfma_f32_16x16x32_bf16 v[92:95], v[76:79], v[84:87], v[60:63]
	s_add_i32 s1, s18, s0
	s_lshl_b32 s1, s1, 7
	s_and_b32 s1, s1, 0x80
	s_nop 2
	v_or_b32_e32 v60, s1, v191
	v_lshl_add_u32 v68, v60, 8, 0
	v_add_u32_e32 v60, v68, v147
	v_add_u32_e32 v64, v68, v148
	v_add_u32_e32 v69, v68, v149
	v_add_u32_e32 v76, v68, v150
	ds_read_b128 v[60:63], v60
	ds_read_b128 v[64:67], v64
	ds_read_b128 v[68:71], v69
	ds_read_b128 v[76:79], v76
	s_waitcnt lgkmcnt(7)
	v_mfma_f32_16x16x32_bf16 v[88:91], v[88:91], v[56:59], 0
	s_waitcnt lgkmcnt(6)
	v_mfma_f32_16x16x32_bf16 v[88:91], v[220:223], v[72:75], v[88:91]
	s_waitcnt lgkmcnt(5)
	v_mfma_f32_16x16x32_bf16 v[88:91], v[224:227], v[80:83], v[88:91]
	s_waitcnt lgkmcnt(4)
	v_mfma_f32_16x16x32_bf16 v[88:91], v[228:231], v[84:87], v[88:91]
	v_readlane_b32 s1, v255, 23
	s_add_i32 s1, s1, s0
	s_lshl_b32 s1, s1, 7
	s_and_b32 s1, s1, 0x80
	v_or_b32_e32 v109, s1, v204
	v_lshl_add_u32 v109, v109, 8, 0
	v_add_u32_e32 v111, v109, v147
	v_add_u32_e32 v196, v109, v148
	ds_read_b128 v[220:223], v111
	ds_read_b128 v[224:227], v196
	v_add_u32_e32 v111, v109, v149
	v_add_u32_e32 v109, v109, v150
	ds_read_b128 v[228:231], v111
	ds_read_b128 v[238:241], v109
	s_waitcnt lgkmcnt(7)
	v_mfma_f32_16x16x32_bf16 v[60:63], v[60:63], v[56:59], 0
	s_waitcnt lgkmcnt(6)
	v_mfma_f32_16x16x32_bf16 v[60:63], v[64:67], v[72:75], v[60:63]
	s_waitcnt lgkmcnt(5)
	v_mfma_f32_16x16x32_bf16 v[60:63], v[68:71], v[80:83], v[60:63]
	s_waitcnt lgkmcnt(4)
	v_mfma_f32_16x16x32_bf16 v[76:79], v[76:79], v[84:87], v[60:63]
	s_add_i32 s1, s19, s0
	s_lshl_b32 s1, s1, 7
	s_and_b32 s1, s1, 0x80
	s_nop 2
	v_or_b32_e32 v60, s1, v205
	v_lshl_add_u32 v68, v60, 8, 0
	v_add_u32_e32 v60, v68, v147
	v_add_u32_e32 v64, v68, v148
	v_add_u32_e32 v69, v68, v149
	ds_read_b128 v[60:63], v60
	ds_read_b128 v[64:67], v64
	v_add_u32_e32 v68, v68, v150
	ds_read_b128 v[242:245], v69
	ds_read_b128 v[246:249], v68
	s_waitcnt lgkmcnt(7)
	v_mfma_f32_16x16x32_bf16 v[68:71], v[220:223], v[56:59], 0
	s_waitcnt lgkmcnt(6)
	v_mfma_f32_16x16x32_bf16 v[68:71], v[224:227], v[72:75], v[68:71]
	s_waitcnt lgkmcnt(5)
	v_mfma_f32_16x16x32_bf16 v[68:71], v[228:231], v[80:83], v[68:71]
	s_waitcnt lgkmcnt(4)
	v_mfma_f32_16x16x32_bf16 v[68:71], v[238:241], v[84:87], v[68:71]
	v_readlane_b32 s1, v255, 25
	s_add_i32 s1, s1, s0
	s_lshl_b32 s1, s1, 7
	s_and_b32 s1, s1, 0x80
	v_or_b32_e32 v109, s1, v206
	v_lshl_add_u32 v109, v109, 8, 0
	v_add_u32_e32 v111, v109, v147
	v_add_u32_e32 v196, v109, v148
	ds_read_b128 v[220:223], v111
	ds_read_b128 v[224:227], v196
	v_add_u32_e32 v111, v109, v149
	v_add_u32_e32 v109, v109, v150
	ds_read_b128 v[228:231], v111
	ds_read_b128 v[238:241], v109
	s_waitcnt lgkmcnt(7)
	v_mfma_f32_16x16x32_bf16 v[60:63], v[60:63], v[56:59], 0
	s_waitcnt lgkmcnt(6)
	v_mfma_f32_16x16x32_bf16 v[60:63], v[64:67], v[72:75], v[60:63]
	s_waitcnt lgkmcnt(5)
	v_mfma_f32_16x16x32_bf16 v[60:63], v[242:245], v[80:83], v[60:63]
	s_waitcnt lgkmcnt(4)
	v_mfma_f32_16x16x32_bf16 v[64:67], v[246:249], v[84:87], v[60:63]
	s_add_i32 s0, s20, s0
	s_lshl_b32 s0, s0, 7
	s_and_b32 s0, s0, 0x80
	s_nop 2
	v_or_b32_e32 v60, s0, v207
	v_lshl_add_u32 v60, v60, 8, 0
	v_add_u32_e32 v61, v60, v147
	v_add_u32_e32 v62, v60, v148
	ds_read_b128 v[242:245], v61
	ds_read_b128 v[246:249], v62
	v_add_u32_e32 v61, v60, v149
	v_add_u32_e32 v60, v60, v150
	ds_read_b128 v[250:253], v61
	ds_read_b128 v[196:199], v60
	s_waitcnt lgkmcnt(7)
	v_mfma_f32_16x16x32_bf16 v[60:63], v[220:223], v[56:59], 0
	s_waitcnt lgkmcnt(6)
	v_mfma_f32_16x16x32_bf16 v[60:63], v[224:227], v[72:75], v[60:63]
	s_waitcnt lgkmcnt(5)
	v_mfma_f32_16x16x32_bf16 v[60:63], v[228:231], v[80:83], v[60:63]
	s_waitcnt lgkmcnt(4)
	v_mfma_f32_16x16x32_bf16 v[60:63], v[238:241], v[84:87], v[60:63]
	s_waitcnt lgkmcnt(3)
	v_mfma_f32_16x16x32_bf16 v[56:59], v[242:245], v[56:59], 0
	s_waitcnt lgkmcnt(2)
	v_mfma_f32_16x16x32_bf16 v[56:59], v[246:249], v[72:75], v[56:59]
	s_waitcnt lgkmcnt(1)
	v_mfma_f32_16x16x32_bf16 v[56:59], v[250:253], v[80:83], v[56:59]
	s_waitcnt lgkmcnt(0)
	v_mfma_f32_16x16x32_bf16 v[56:59], v[196:199], v[84:87], v[56:59]
	v_mov_b32_e32 v246, 0xf149f2ca
	ds_read_b32 v40, v151
	ds_read_b32 v41, v152
	ds_read_b32 v42, v153
	ds_read_b32 v43, v154
	ds_read_b32 v44, v155
	ds_read_b32 v45, v157
	ds_read_b32 v46, v158
	ds_read_b32 v47, v159
	ds_read_b32 v48, v160
	ds_read_b32 v49, v161
	ds_read_b32 v50, v162
	ds_read_b32 v51, v163
	ds_read_b32 v52, v164
	ds_read_b32 v53, v165
	ds_read_b32 v54, v166
	ds_read_b32 v55, v167
	ds_read_b32 v220, v168
	ds_read_b32 v221, v169
	ds_read_b32 v222, v170
	ds_read_b32 v223, v171
	ds_read_b32 v224, v172
	ds_read_b32 v225, v173
	ds_read_b32 v226, v174
	ds_read_b32 v227, v175
	ds_read_b32 v228, v176
	ds_read_b32 v229, v177
	ds_read_b32 v230, v178
	ds_read_b32 v231, v179
	ds_read_b32 v238, v180
	ds_read_b32 v239, v181
	ds_read_b32 v240, v182
	ds_read_b32 v241, v183
	ds_read_b32 v242, v156
	ds_read_b32 v243, v184
	ds_read_b32 v244, v185
	ds_read_b32 v245, v186
	s_cmp_lg_u32 s39, 0
	v_readlane_b32 s10, v255, 29
	s_cselect_b64 s[0:1], -1, 0
	v_readlane_b32 s11, v255, 30
	v_readlane_b32 s40, v255, 27
	s_or_b64 s[10:11], s[0:1], s[10:11]
	v_readlane_b32 s41, v255, 28
	s_and_b64 s[40:41], s[40:41], s[10:11]
	s_waitcnt lgkmcnt(0)
	v_add_f32_e32 v81, v100, v40
	v_cndmask_b32_e64 v81, v246, v81, s[40:41]
	v_readlane_b32 s10, v255, 33
	v_readlane_b32 s11, v255, 34
	v_readlane_b32 s40, v255, 31
	s_or_b64 s[10:11], s[0:1], s[10:11]
	v_readlane_b32 s41, v255, 32
	s_and_b64 s[40:41], s[40:41], s[10:11]
	v_add_f32_e32 v75, v101, v41
	v_cndmask_b32_e64 v75, v246, v75, s[40:41]
	v_readlane_b32 s10, v255, 37
	v_readlane_b32 s11, v255, 38
	v_readlane_b32 s40, v255, 35
	s_or_b64 s[10:11], s[0:1], s[10:11]
	v_readlane_b32 s41, v255, 36
	s_and_b64 s[40:41], s[40:41], s[10:11]
	v_add_f32_e32 v85, v102, v42
	v_cndmask_b32_e64 v85, v246, v85, s[40:41]
	v_readlane_b32 s10, v255, 41
	v_readlane_b32 s11, v255, 42
	v_readlane_b32 s40, v255, 39
	s_or_b64 s[10:11], s[0:1], s[10:11]
	v_readlane_b32 s41, v255, 40
	s_and_b64 s[40:41], s[40:41], s[10:11]
	v_add_f32_e32 v82, v103, v43
	v_cndmask_b32_e64 v82, v246, v82, s[40:41]
	v_readlane_b32 s10, v255, 43
	v_readlane_b32 s11, v255, 44
	s_or_b64 s[40:41], s[0:1], s[10:11]
	v_add_f32_e32 v100, v96, v44
	v_cndmask_b32_e64 v100, v246, v100, s[40:41]
	v_readlane_b32 s10, v255, 45
	v_readlane_b32 s11, v255, 46
	s_or_b64 s[40:41], s[0:1], s[10:11]
	v_add_f32_e32 v86, v97, v45
	v_cndmask_b32_e64 v86, v246, v86, s[40:41]
	v_readlane_b32 s10, v255, 47
	v_readlane_b32 s11, v255, 48
	s_or_b64 s[40:41], s[0:1], s[10:11]
	v_add_f32_e32 v96, v98, v46
	v_cndmask_b32_e64 v96, v246, v96, s[40:41]
	v_readlane_b32 s10, v255, 49
	v_readlane_b32 s11, v255, 50
	s_or_b64 s[40:41], s[0:1], s[10:11]
	v_add_f32_e32 v80, v99, v47
	v_cndmask_b32_e64 v80, v246, v80, s[40:41]
	v_readlane_b32 s10, v255, 51
	v_readlane_b32 s11, v255, 52
	s_or_b64 s[40:41], s[0:1], s[10:11]
	v_add_f32_e32 v84, v92, v48
	v_cndmask_b32_e64 v84, v246, v84, s[40:41]
	v_readlane_b32 s10, v255, 53
	v_readlane_b32 s11, v255, 54
	s_or_b64 s[40:41], s[0:1], s[10:11]
	v_add_f32_e32 v83, v93, v49
	v_cndmask_b32_e64 v83, v246, v83, s[40:41]
	v_readlane_b32 s10, v255, 55
	v_readlane_b32 s11, v255, 56
	s_or_b64 s[40:41], s[0:1], s[10:11]
	v_add_f32_e32 v92, v94, v50
	v_cndmask_b32_e64 v92, v246, v92, s[40:41]
	v_readlane_b32 s10, v255, 57
	v_readlane_b32 s11, v255, 58
	s_or_b64 s[40:41], s[0:1], s[10:11]
	v_add_f32_e32 v87, v95, v51
	v_cndmask_b32_e64 v87, v246, v87, s[40:41]
	v_readlane_b32 s10, v255, 59
	v_readlane_b32 s11, v255, 60
	s_or_b64 s[40:41], s[0:1], s[10:11]
	v_add_f32_e32 v94, v88, v52
	v_cndmask_b32_e64 v94, v246, v94, s[40:41]
	v_readlane_b32 s10, v255, 61
	v_readlane_b32 s11, v255, 62
	s_or_b64 s[40:41], s[0:1], s[10:11]
	v_add_f32_e32 v93, v89, v53
	v_cndmask_b32_e64 v93, v246, v93, s[40:41]
	s_or_b64 s[40:41], s[0:1], s[52:53]
	v_add_f32_e32 v95, v90, v54
	v_cndmask_b32_e64 v95, v246, v95, s[40:41]
	s_or_b64 s[40:41], s[0:1], s[54:55]
	v_add_f32_e32 v88, v91, v55
	v_cndmask_b32_e64 v88, v246, v88, s[40:41]
	s_or_b64 s[40:41], s[0:1], s[56:57]
	v_add_f32_e32 v90, v76, v220
	v_cndmask_b32_e64 v90, v246, v90, s[40:41]
	s_or_b64 s[40:41], s[0:1], s[58:59]
	v_add_f32_e32 v89, v77, v221
	v_cndmask_b32_e64 v89, v246, v89, s[40:41]
	s_or_b64 s[40:41], s[0:1], s[60:61]
	v_add_f32_e32 v91, v78, v222
	v_cndmask_b32_e64 v91, v246, v91, s[40:41]
	s_or_b64 s[40:41], s[0:1], s[62:63]
	v_add_f32_e32 v76, v79, v223
	v_cndmask_b32_e64 v76, v246, v76, s[40:41]
	s_or_b64 s[40:41], s[0:1], s[64:65]
	v_add_f32_e32 v78, v68, v224
	v_cndmask_b32_e64 v78, v246, v78, s[40:41]
	s_or_b64 s[40:41], s[0:1], s[66:67]
	v_add_f32_e32 v77, v69, v225
	v_cndmask_b32_e64 v77, v246, v77, s[40:41]
	s_or_b64 s[40:41], s[0:1], s[68:69]
	v_add_f32_e32 v79, v70, v226
	v_cndmask_b32_e64 v79, v246, v79, s[40:41]
	s_or_b64 s[40:41], s[0:1], s[70:71]
	v_add_f32_e32 v68, v71, v227
	v_cndmask_b32_e64 v68, v246, v68, s[40:41]
	s_or_b64 s[40:41], s[0:1], s[72:73]
	v_add_f32_e32 v70, v64, v228
	v_cndmask_b32_e64 v70, v246, v70, s[40:41]
	s_or_b64 s[40:41], s[0:1], s[74:75]
	v_add_f32_e32 v69, v65, v229
	v_cndmask_b32_e64 v69, v246, v69, s[40:41]
	s_or_b64 s[40:41], s[0:1], s[76:77]
	v_add_f32_e32 v71, v66, v230
	v_cndmask_b32_e64 v71, v246, v71, s[40:41]
	s_or_b64 s[40:41], s[0:1], s[78:79]
	v_add_f32_e32 v64, v67, v231
	v_cndmask_b32_e64 v64, v246, v64, s[40:41]
	s_or_b64 s[40:41], s[0:1], s[80:81]
	v_add_f32_e32 v66, v60, v238
	v_cndmask_b32_e64 v66, v246, v66, s[40:41]
	s_or_b64 s[40:41], s[0:1], s[82:83]
	v_add_f32_e32 v65, v61, v239
	v_cndmask_b32_e64 v65, v246, v65, s[40:41]
	s_or_b64 s[40:41], s[0:1], s[84:85]
	v_add_f32_e32 v61, v62, v240
	v_cndmask_b32_e64 v61, v246, v61, s[40:41]
	s_or_b64 s[40:41], s[0:1], s[86:87]
	v_add_f32_e32 v60, v63, v241
	v_cndmask_b32_e64 v60, v246, v60, s[40:41]
	s_or_b64 s[10:11], s[0:1], s[90:91]
	s_and_b64 s[40:41], s[88:89], s[10:11]
	v_add_f32_e32 v63, v56, v242
	v_cndmask_b32_e64 v63, v246, v63, s[40:41]
	s_or_b64 s[10:11], s[0:1], s[94:95]
	s_and_b64 s[40:41], s[92:93], s[10:11]
	v_add_f32_e32 v62, v57, v243
	v_cndmask_b32_e64 v62, v246, v62, s[40:41]
	s_or_b64 s[10:11], s[0:1], s[8:9]
	s_and_b64 s[40:41], s[96:97], s[10:11]
	v_add_f32_e32 v57, v58, v244
	v_cndmask_b32_e64 v57, v246, v57, s[40:41]
	s_or_b64 s[0:1], s[0:1], s[6:7]
	s_and_b64 s[10:11], s[4:5], s[0:1]
	v_add_f32_e32 v56, v59, v245
	v_cndmask_b32_e64 v56, v246, v56, s[10:11]
	s_mov_b32 s0, 0xff61b1e6
	v_max3_f32 v58, v81, s0, v75
	v_max3_f32 v58, v58, v85, v82
	v_max3_f32 v58, v58, v100, v86
	v_max3_f32 v58, v58, v96, v80
	v_max3_f32 v58, v58, v84, v83
	v_max3_f32 v58, v58, v92, v87
	v_max3_f32 v58, v58, v94, v93
	v_max3_f32 v58, v58, v95, v88
	v_max3_f32 v58, v58, v90, v89
	v_max3_f32 v58, v58, v91, v76
	v_max3_f32 v58, v58, v78, v77
	v_max3_f32 v58, v58, v79, v68
	v_max3_f32 v58, v58, v70, v69
	v_max3_f32 v58, v58, v71, v64
	v_max3_f32 v58, v58, v66, v65
	v_max3_f32 v58, v58, v61, v60
	v_max3_f32 v67, v58, v63, v62
	s_lshr_b32 s0, vcc_lo, s35
	v_lshl_add_u32 v58, s39, 7, v145
	v_ashrrev_i32_e32 v59, 31, v58
	s_add_u32 s0, s2, s0
	s_addc_u32 s1, s3, 0
	v_lshlrev_b64 v[58:59], s34, v[58:59]
	v_lshl_add_u64 v[72:73], s[0:1], 0, v[58:59]
	v_max3_f32 v58, v67, v57, v56
	v_mov_b32_e32 v59, v58
	s_add_i32 s0, s39, 1
	v_readlane_b32 s10, v255, 13
	s_add_i32 s1, s0, s33
	s_add_i32 s10, s0, s10
	s_waitcnt lgkmcnt(0)
	s_nop 1
	v_permlane16_swap_b32_e32 v59, v58
	v_max_f32_e32 v59, v59, v59
	v_max_f32_e32 v58, v58, v59
	v_mov_b32_e32 v59, v58
	s_lshl_b32 s1, s1, 15
	s_lshl_b32 s10, s10, 15
	s_and_b32 s1, s1, 0x8000
	s_and_b32 s10, s10, 0x8000
	s_waitcnt lgkmcnt(0)
	s_nop 1
	v_permlane32_swap_b32_e32 v59, v58
	v_max_f32_e32 v59, v59, v59
	v_max_f32_e32 v74, v58, v59
	v_sub_f32_e32 v58, v81, v74
	v_exp_f32_e32 v58, v58
	v_sub_f32_e32 v67, v75, v74
	v_exp_f32_e32 v67, v67
	v_sub_f32_e32 v75, v85, v74
	v_exp_f32_e32 v81, v75
	v_sub_f32_e32 v75, v82, v74
	v_exp_f32_e32 v82, v75
	v_sub_f32_e32 v75, v100, v74
	v_add_f32_e32 v59, 0, v58
	v_exp_f32_e32 v85, v75
	v_sub_f32_e32 v75, v86, v74
	v_add_f32_e32 v59, v67, v59
	v_exp_f32_e32 v86, v75
	v_sub_f32_e32 v75, v96, v74
	v_add_f32_e32 v59, v81, v59
	v_exp_f32_e32 v96, v75
	v_sub_f32_e32 v75, v80, v74
	v_add_f32_e32 v59, v82, v59
	v_exp_f32_e32 v97, v75
	v_sub_f32_e32 v75, v84, v74
	v_add_f32_e32 v59, v85, v59
	v_exp_f32_e32 v84, v75
	v_sub_f32_e32 v75, v83, v74
	v_add_f32_e32 v59, v86, v59
	v_exp_f32_e32 v83, v75
	v_sub_f32_e32 v75, v92, v74
	v_add_f32_e32 v59, v96, v59
	v_exp_f32_e32 v92, v75
	v_sub_f32_e32 v75, v87, v74
	v_add_f32_e32 v59, v97, v59
	v_exp_f32_e32 v87, v75
	v_sub_f32_e32 v75, v94, v74
	v_add_f32_e32 v59, v84, v59
	v_exp_f32_e32 v94, v75
	v_sub_f32_e32 v75, v93, v74
	v_add_f32_e32 v59, v83, v59
	v_exp_f32_e32 v93, v75
	v_sub_f32_e32 v75, v95, v74
	v_add_f32_e32 v59, v92, v59
	v_exp_f32_e32 v95, v75
	v_sub_f32_e32 v75, v88, v74
	v_add_f32_e32 v59, v87, v59
	v_exp_f32_e32 v88, v75
	v_sub_f32_e32 v75, v90, v74
	v_add_f32_e32 v59, v94, v59
	v_exp_f32_e32 v90, v75
	v_sub_f32_e32 v75, v89, v74
	v_add_f32_e32 v59, v93, v59
	v_exp_f32_e32 v89, v75
	v_sub_f32_e32 v75, v91, v74
	v_add_f32_e32 v59, v95, v59
	v_exp_f32_e32 v91, v75
	v_sub_f32_e32 v75, v76, v74
	v_add_f32_e32 v59, v88, v59
	v_exp_f32_e32 v98, v75
	v_sub_f32_e32 v75, v78, v74
	v_add_f32_e32 v59, v90, v59
	v_exp_f32_e32 v99, v75
	v_sub_f32_e32 v75, v77, v74
	v_add_f32_e32 v59, v89, v59
	v_exp_f32_e32 v77, v75
	v_sub_f32_e32 v75, v79, v74
	v_add_f32_e32 v59, v91, v59
	v_exp_f32_e32 v100, v75
	v_sub_f32_e32 v68, v68, v74
	v_add_f32_e32 v59, v98, v59
	v_exp_f32_e32 v101, v68
	v_sub_f32_e32 v68, v70, v74
	v_add_f32_e32 v59, v99, v59
	v_exp_f32_e32 v102, v68
	v_sub_f32_e32 v68, v69, v74
	v_add_f32_e32 v59, v77, v59
	v_exp_f32_e32 v103, v68
	v_sub_f32_e32 v68, v71, v74
	v_add_f32_e32 v59, v100, v59
	v_exp_f32_e32 v109, v68
	v_sub_f32_e32 v64, v64, v74
	v_add_f32_e32 v59, v101, v59
	v_exp_f32_e32 v111, v64
	v_sub_f32_e32 v64, v66, v74
	v_add_f32_e32 v59, v102, v59
	v_exp_f32_e32 v196, v64
	v_sub_f32_e32 v64, v65, v74
	v_add_f32_e32 v59, v103, v59
	v_exp_f32_e32 v197, v64
	v_sub_f32_e32 v61, v61, v74
	v_add_f32_e32 v59, v109, v59
	v_exp_f32_e32 v198, v61
	v_sub_f32_e32 v60, v60, v74
	v_add_f32_e32 v59, v111, v59
	v_exp_f32_e32 v199, v60
	v_sub_f32_e32 v60, v63, v74
	v_add_f32_e32 v59, v196, v59
	v_exp_f32_e32 v220, v60
	v_sub_f32_e32 v60, v62, v74
	v_add_f32_e32 v59, v197, v59
	v_exp_f32_e32 v221, v60
	v_sub_f32_e32 v57, v57, v74
	v_add_f32_e32 v59, v198, v59
	v_exp_f32_e32 v57, v57
	v_sub_f32_e32 v56, v56, v74
	v_add_f32_e32 v59, v199, v59
	v_exp_f32_e32 v222, v56
	v_add_f32_e32 v59, v220, v59
	v_add_f32_e32 v59, v221, v59
	v_add_f32_e32 v59, v57, v59
	v_add_f32_e32 v56, v222, v59
	ds_bpermute_b32 v59, v218, v56
	v_readlane_b32 s11, v255, 15
	s_add_i32 s1, s16, s1
	s_add_i32 s10, s11, s10
	v_cvt_pk_bf16_f32 v78, v58, v67
	v_cvt_pk_bf16_f32 v79, v81, v82
	v_cvt_pk_bf16_f32 v80, v85, v86
	v_cvt_pk_bf16_f32 v81, v96, v97
	v_cvt_pk_bf16_f32 v68, v84, v83
	v_cvt_pk_bf16_f32 v69, v92, v87
	v_cvt_pk_bf16_f32 v70, v94, v93
	v_cvt_pk_bf16_f32 v71, v95, v88
	v_cvt_pk_bf16_f32 v64, v90, v89
	v_cvt_pk_bf16_f32 v65, v91, v98
	v_cvt_pk_bf16_f32 v66, v99, v77
	v_add_u32_e32 v77, s1, v129
	v_add_u32_e32 v84, s10, v129
	s_waitcnt lgkmcnt(0)
	v_add_f32_e32 v75, v56, v59
	v_cvt_pk_bf16_f32 v67, v100, v101
	v_cvt_pk_bf16_f32 v60, v102, v103
	v_cvt_pk_bf16_f32 v61, v109, v111
	v_cvt_pk_bf16_f32 v62, v196, v197
	v_cvt_pk_bf16_f32 v63, v198, v199
	v_cvt_pk_bf16_f32 v56, v220, v221
	v_cvt_pk_bf16_f32 v57, v57, v222
	v_cvt_pk_bf16_f32 v58, v193, v193
	v_cvt_pk_bf16_f32 v59, v193, v193
	ds_read_b64_tr_b16 v[82:83], v77
	ds_read_b64_tr_b16 v[84:85], v84
	v_add_u32_e32 v77, s1, v130
	v_add_u32_e32 v88, s10, v130
	ds_read_b64_tr_b16 v[86:87], v77
	ds_read_b64_tr_b16 v[88:89], v88
	v_add_u32_e32 v77, s1, v131
	v_add_u32_e32 v92, s10, v131
	ds_read_b64_tr_b16 v[90:91], v77
	ds_read_b64_tr_b16 v[92:93], v92
	v_add_u32_e32 v77, s1, v132
	v_add_u32_e32 v96, s10, v132
	ds_read_b64_tr_b16 v[94:95], v77
	ds_read_b64_tr_b16 v[96:97], v96
	ds_bpermute_b32 v76, v219, v75
	s_waitcnt lgkmcnt(7)
	v_mfma_f32_16x16x32_bf16 v[82:85], v[82:85], v[78:81], 0
	s_waitcnt lgkmcnt(5)
	v_mfma_f32_16x16x32_bf16 v[86:89], v[86:89], v[78:81], 0
	v_add_u32_e32 v77, s1, v133
	v_add_u32_e32 v100, s10, v133
	v_add_u32_e32 v102, s1, v134
	v_add_u32_e32 v103, s10, v134
	ds_read_b64_tr_b16 v[98:99], v77
	ds_read_b64_tr_b16 v[100:101], v100
	ds_read_b64_tr_b16 v[196:197], v102
	ds_read_b64_tr_b16 v[198:199], v103
	s_waitcnt lgkmcnt(7)
	v_mfma_f32_16x16x32_bf16 v[90:93], v[90:93], v[78:81], 0
	s_waitcnt lgkmcnt(5)
	v_mfma_f32_16x16x32_bf16 v[94:97], v[94:97], v[78:81], 0
	v_add_u32_e32 v77, s1, v135
	v_add_u32_e32 v102, s10, v135
	v_add_u32_e32 v103, s1, v136
	v_add_u32_e32 v109, s10, v136
	ds_read_b64_tr_b16 v[220:221], v77
	ds_read_b64_tr_b16 v[222:223], v102
	ds_read_b64_tr_b16 v[224:225], v103
	ds_read_b64_tr_b16 v[226:227], v109
	s_waitcnt lgkmcnt(6)
	v_mfma_f32_16x16x32_bf16 v[98:101], v[98:101], v[78:81], 0
	s_waitcnt lgkmcnt(4)
	v_mfma_f32_16x16x32_bf16 v[196:199], v[196:199], v[78:81], 0
	s_add_i32 s1, s0, s17
	s_lshl_b32 s1, s1, 15
	s_add_i32 s10, s0, s21
	s_and_b32 s1, s1, 0x8000
	s_lshl_b32 s10, s10, 15
	s_and_b32 s10, s10, 0x8000
	s_add_i32 s1, s22, s1
	s_add_i32 s10, s23, s10
	v_add_u32_e32 v77, s1, v129
	v_add_u32_e32 v102, s10, v129
	v_add_u32_e32 v103, s1, v130
	v_add_u32_e32 v109, s10, v130
	ds_read_b64_tr_b16 v[228:229], v77
	ds_read_b64_tr_b16 v[230:231], v102
	ds_read_b64_tr_b16 v[238:239], v103
	ds_read_b64_tr_b16 v[240:241], v109
	s_waitcnt lgkmcnt(6)
	v_mfma_f32_16x16x32_bf16 v[220:223], v[220:223], v[78:81], 0
	s_waitcnt lgkmcnt(4)
	v_mfma_f32_16x16x32_bf16 v[78:81], v[224:227], v[78:81], 0
	v_add_u32_e32 v77, s1, v131
	v_add_u32_e32 v102, s10, v131
	v_add_u32_e32 v103, s1, v132
	v_add_u32_e32 v109, s10, v132
	ds_read_b64_tr_b16 v[224:225], v77
	ds_read_b64_tr_b16 v[226:227], v102
	ds_read_b64_tr_b16 v[242:243], v103
	ds_read_b64_tr_b16 v[244:245], v109
	s_waitcnt lgkmcnt(6)
	v_mfma_f32_16x16x32_bf16 v[82:85], v[228:231], v[68:71], v[82:85]
	s_waitcnt lgkmcnt(4)
	v_mfma_f32_16x16x32_bf16 v[86:89], v[238:241], v[68:71], v[86:89]
	v_add_u32_e32 v77, s1, v133
	v_add_u32_e32 v102, s10, v133
	v_add_u32_e32 v103, s1, v134
	v_add_u32_e32 v109, s10, v134
	ds_read_b64_tr_b16 v[228:229], v77
	ds_read_b64_tr_b16 v[230:231], v102
	ds_read_b64_tr_b16 v[238:239], v103
	ds_read_b64_tr_b16 v[240:241], v109
	s_waitcnt lgkmcnt(6)
	v_mfma_f32_16x16x32_bf16 v[90:93], v[224:227], v[68:71], v[90:93]
	s_waitcnt lgkmcnt(4)
	v_mfma_f32_16x16x32_bf16 v[94:97], v[242:245], v[68:71], v[94:97]
	v_add_u32_e32 v77, s1, v135
	v_add_u32_e32 v102, s10, v135
	v_add_u32_e32 v103, s1, v136
	v_add_u32_e32 v109, s10, v136
	ds_read_b64_tr_b16 v[224:225], v77
	ds_read_b64_tr_b16 v[226:227], v102
	ds_read_b64_tr_b16 v[242:243], v103
	ds_read_b64_tr_b16 v[244:245], v109
	s_waitcnt lgkmcnt(6)
	v_mfma_f32_16x16x32_bf16 v[98:101], v[228:231], v[68:71], v[98:101]
	s_waitcnt lgkmcnt(4)
	v_mfma_f32_16x16x32_bf16 v[196:199], v[238:241], v[68:71], v[196:199]
	s_add_i32 s1, s0, s18
	s_lshl_b32 s1, s1, 15
	s_add_i32 s10, s0, s24
	s_and_b32 s1, s1, 0x8000
	s_lshl_b32 s10, s10, 15
	s_and_b32 s10, s10, 0x8000
	s_add_i32 s1, s25, s1
	s_add_i32 s10, s26, s10
	v_add_u32_e32 v77, s1, v129
	v_add_u32_e32 v102, s10, v129
	v_add_u32_e32 v103, s1, v130
	v_add_u32_e32 v109, s10, v130
	ds_read_b64_tr_b16 v[228:229], v77
	ds_read_b64_tr_b16 v[230:231], v102
	ds_read_b64_tr_b16 v[238:239], v103
	ds_read_b64_tr_b16 v[240:241], v109
	s_waitcnt lgkmcnt(6)
	v_mfma_f32_16x16x32_bf16 v[220:223], v[224:227], v[68:71], v[220:223]
	s_waitcnt lgkmcnt(4)
	v_mfma_f32_16x16x32_bf16 v[68:71], v[242:245], v[68:71], v[78:81]
	v_add_u32_e32 v77, s1, v131
	s_nop 1
	v_add_u32_e32 v80, s10, v131
	v_add_u32_e32 v102, s1, v132
	v_add_u32_e32 v103, s10, v132
	ds_read_b64_tr_b16 v[78:79], v77
	ds_read_b64_tr_b16 v[80:81], v80
	ds_read_b64_tr_b16 v[224:225], v102
	ds_read_b64_tr_b16 v[226:227], v103
	s_waitcnt lgkmcnt(6)
	v_mfma_f32_16x16x32_bf16 v[82:85], v[228:231], v[64:67], v[82:85]
	s_waitcnt lgkmcnt(4)
	v_mfma_f32_16x16x32_bf16 v[86:89], v[238:241], v[64:67], v[86:89]
	v_add_u32_e32 v77, s1, v133
	v_add_u32_e32 v102, s10, v133
	v_add_u32_e32 v103, s1, v134
	v_add_u32_e32 v109, s10, v134
	ds_read_b64_tr_b16 v[228:229], v77
	ds_read_b64_tr_b16 v[230:231], v102
	ds_read_b64_tr_b16 v[238:239], v103
	ds_read_b64_tr_b16 v[240:241], v109
	s_waitcnt lgkmcnt(6)
	v_mfma_f32_16x16x32_bf16 v[78:81], v[78:81], v[64:67], v[90:93]
	s_waitcnt lgkmcnt(4)
	v_mfma_f32_16x16x32_bf16 v[90:93], v[224:227], v[64:67], v[94:97]
	v_add_u32_e32 v77, s1, v135
	s_nop 1
	v_add_u32_e32 v96, s10, v135
	v_add_u32_e32 v102, s1, v136
	v_add_u32_e32 v103, s10, v136
	ds_read_b64_tr_b16 v[94:95], v77
	ds_read_b64_tr_b16 v[96:97], v96
	ds_read_b64_tr_b16 v[224:225], v102
	ds_read_b64_tr_b16 v[226:227], v103
	s_waitcnt lgkmcnt(6)
	v_mfma_f32_16x16x32_bf16 v[98:101], v[228:231], v[64:67], v[98:101]
	s_waitcnt lgkmcnt(4)
	v_mfma_f32_16x16x32_bf16 v[196:199], v[238:241], v[64:67], v[196:199]
	s_add_i32 s1, s0, s19
	s_lshl_b32 s1, s1, 15
	s_add_i32 s10, s0, s27
	s_and_b32 s1, s1, 0x8000
	s_lshl_b32 s10, s10, 15
	s_and_b32 s10, s10, 0x8000
	s_add_i32 s1, s28, s1
	s_add_i32 s10, s29, s10
	v_add_u32_e32 v77, s1, v129
	v_add_u32_e32 v102, s10, v129
	v_add_u32_e32 v103, s1, v130
	v_add_u32_e32 v109, s10, v130
	ds_read_b64_tr_b16 v[228:229], v77
	ds_read_b64_tr_b16 v[230:231], v102
	ds_read_b64_tr_b16 v[238:239], v103
	ds_read_b64_tr_b16 v[240:241], v109
	s_waitcnt lgkmcnt(6)
	v_mfma_f32_16x16x32_bf16 v[94:97], v[94:97], v[64:67], v[220:223]
	s_waitcnt lgkmcnt(4)
	v_mfma_f32_16x16x32_bf16 v[64:67], v[224:227], v[64:67], v[68:71]
	s_nop 2
	v_add_u32_e32 v68, s1, v131
	v_add_u32_e32 v70, s10, v131
	v_add_u32_e32 v77, s1, v132
	v_add_u32_e32 v102, s10, v132
	ds_read_b64_tr_b16 v[68:69], v68
	ds_read_b64_tr_b16 v[70:71], v70
	ds_read_b64_tr_b16 v[220:221], v77
	ds_read_b64_tr_b16 v[222:223], v102
	s_waitcnt lgkmcnt(6)
	v_mfma_f32_16x16x32_bf16 v[82:85], v[228:231], v[60:63], v[82:85]
	s_waitcnt lgkmcnt(4)
	v_mfma_f32_16x16x32_bf16 v[86:89], v[238:241], v[60:63], v[86:89]
	v_add_u32_e32 v77, s1, v133
	v_add_u32_e32 v102, s10, v133
	v_add_u32_e32 v103, s1, v134
	v_add_u32_e32 v109, s10, v134
	ds_read_b64_tr_b16 v[224:225], v77
	ds_read_b64_tr_b16 v[226:227], v102
	ds_read_b64_tr_b16 v[228:229], v103
	ds_read_b64_tr_b16 v[230:231], v109
	s_waitcnt lgkmcnt(6)
	v_mfma_f32_16x16x32_bf16 v[68:71], v[68:71], v[60:63], v[78:81]
	s_waitcnt lgkmcnt(4)
	v_mfma_f32_16x16x32_bf16 v[78:81], v[220:223], v[60:63], v[90:93]
	v_add_u32_e32 v77, s1, v135
	s_nop 1
	v_add_u32_e32 v92, s10, v135
	v_add_u32_e32 v102, s1, v136
	v_add_u32_e32 v103, s10, v136
	ds_read_b64_tr_b16 v[90:91], v77
	ds_read_b64_tr_b16 v[92:93], v92
	ds_read_b64_tr_b16 v[220:221], v102
	ds_read_b64_tr_b16 v[222:223], v103
	s_waitcnt lgkmcnt(6)
	v_mfma_f32_16x16x32_bf16 v[98:101], v[224:227], v[60:63], v[98:101]
	s_waitcnt lgkmcnt(4)
	v_mfma_f32_16x16x32_bf16 v[196:199], v[228:231], v[60:63], v[196:199]
	s_add_i32 s1, s0, s20
	s_lshl_b32 s1, s1, 15
	s_add_i32 s0, s0, s30
	s_and_b32 s1, s1, 0x8000
	s_lshl_b32 s0, s0, 15
	s_and_b32 s0, s0, 0x8000
	s_add_i32 s1, s16, s1
	s_add_i32 s0, s31, s0
	v_add_u32_e32 v77, s1, v129
	v_add_u32_e32 v102, s0, v129
	v_add_u32_e32 v103, s1, v130
	v_add_u32_e32 v109, s0, v130
	ds_read_b64_tr_b16 v[224:225], v77
	ds_read_b64_tr_b16 v[226:227], v102
	ds_read_b64_tr_b16 v[228:229], v103
	ds_read_b64_tr_b16 v[230:231], v109
	s_waitcnt lgkmcnt(6)
	v_mfma_f32_16x16x32_bf16 v[90:93], v[90:93], v[60:63], v[94:97]
	s_waitcnt lgkmcnt(4)
	v_mfma_f32_16x16x32_bf16 v[60:63], v[220:223], v[60:63], v[64:67]
	s_nop 2
	v_add_u32_e32 v64, s1, v131
	v_add_u32_e32 v66, s0, v131
	v_add_u32_e32 v96, s0, v132
	v_add_u32_e32 v77, s1, v132
	ds_read_b64_tr_b16 v[64:65], v64
	ds_read_b64_tr_b16 v[66:67], v66
	ds_read_b64_tr_b16 v[94:95], v77
	ds_read_b64_tr_b16 v[96:97], v96
	s_waitcnt lgkmcnt(6)
	v_mfma_f32_16x16x32_bf16 v[82:85], v[224:227], v[56:59], v[82:85]
	s_waitcnt lgkmcnt(4)
	v_mfma_f32_16x16x32_bf16 v[86:89], v[228:231], v[56:59], v[86:89]
	v_add_u32_e32 v77, s1, v133
	v_add_u32_e32 v102, s0, v133
	v_add_u32_e32 v103, s1, v134
	v_add_u32_e32 v109, s0, v134
	ds_read_b64_tr_b16 v[220:221], v77
	ds_read_b64_tr_b16 v[222:223], v102
	ds_read_b64_tr_b16 v[224:225], v103
	ds_read_b64_tr_b16 v[226:227], v109
	s_waitcnt lgkmcnt(6)
	v_mfma_f32_16x16x32_bf16 v[64:67], v[64:67], v[56:59], v[68:71]
	s_waitcnt lgkmcnt(4)
	v_mfma_f32_16x16x32_bf16 v[68:71], v[94:97], v[56:59], v[78:81]
	v_add_u32_e32 v77, s1, v135
	s_nop 1
	v_add_u32_e32 v80, s0, v135
	v_add_u32_e32 v94, s1, v136
	v_add_u32_e32 v96, s0, v136
	ds_read_b64_tr_b16 v[78:79], v77
	ds_read_b64_tr_b16 v[80:81], v80
	ds_read_b64_tr_b16 v[94:95], v94
	ds_read_b64_tr_b16 v[96:97], v96
	s_waitcnt lgkmcnt(6)
	v_mfma_f32_16x16x32_bf16 v[98:101], v[220:223], v[56:59], v[98:101]
	s_waitcnt lgkmcnt(4)
	v_mfma_f32_16x16x32_bf16 v[196:199], v[224:227], v[56:59], v[196:199]
	s_waitcnt lgkmcnt(2)
	v_mfma_f32_16x16x32_bf16 v[78:81], v[78:81], v[56:59], v[90:93]
	s_waitcnt lgkmcnt(0)
	v_mfma_f32_16x16x32_bf16 v[58:61], v[94:97], v[56:59], v[60:63]
	v_add_f32_e32 v56, v75, v76
	v_div_scale_f32 v57, s[0:1], v56, v56, 1.0
	s_nop 0
	v_rcp_f32_e32 v62, v57
	v_div_scale_f32 v63, vcc, 1.0, v56, 1.0
	v_fma_f32 v75, -v57, v62, 1.0
	v_fmac_f32_e32 v62, v75, v62
	v_mul_f32_e32 v75, v63, v62
	v_fma_f32 v76, -v57, v75, v63
	v_fmac_f32_e32 v75, v76, v62
	v_fma_f32 v57, -v57, v75, v63
	v_div_fmas_f32 v57, v57, v62, v75
	v_div_fixup_f32 v57, v57, v56, 1.0
	v_lshlrev_b64 v[62:63], 12, v[72:73]
	v_mul_f32_e32 v75, v57, v82
	v_mul_f32_e32 v76, v57, v83
	v_mul_f32_e32 v77, v57, v85
	v_lshl_add_u64 v[62:63], v[126:127], 0, v[62:63]
	v_cvt_pk_bf16_f32 v76, v75, v76
	v_mul_f32_e32 v75, v57, v84
	v_cvt_pk_bf16_f32 v77, v75, v77
	global_store_dwordx2 v[62:63], v[76:77], off
	v_mul_f32_e32 v75, v57, v86
	v_mul_f32_e32 v76, v57, v87
	v_mul_f32_e32 v77, v57, v89
	v_mul_f32_e32 v64, v57, v64
	v_mul_f32_e32 v65, v57, v65
	v_cvt_pk_bf16_f32 v76, v75, v76
	v_mul_f32_e32 v75, v57, v88
	v_cvt_pk_bf16_f32 v77, v75, v77
	global_store_dwordx2 v[62:63], v[76:77], off offset:32
	v_cvt_pk_bf16_f32 v64, v64, v65
	v_mul_f32_e32 v65, v57, v66
	v_mul_f32_e32 v66, v57, v67
	v_cvt_pk_bf16_f32 v65, v65, v66
	global_store_dwordx2 v[62:63], v[64:65], off offset:64
	v_mul_f32_e32 v64, v57, v68
	v_mul_f32_e32 v65, v57, v69
	v_cvt_pk_bf16_f32 v64, v64, v65
	v_mul_f32_e32 v65, v57, v70
	v_mul_f32_e32 v66, v57, v71
	v_cvt_pk_bf16_f32 v65, v65, v66
	global_store_dwordx2 v[62:63], v[64:65], off offset:96
	v_mul_f32_e32 v64, v57, v98
	v_mul_f32_e32 v65, v57, v99
	v_cvt_pk_bf16_f32 v64, v64, v65
	v_mul_f32_e32 v65, v57, v100
	v_mul_f32_e32 v66, v57, v101
	v_cvt_pk_bf16_f32 v65, v65, v66
	global_store_dwordx2 v[62:63], v[64:65], off offset:128
	v_mul_f32_e32 v64, v57, v196
	v_mul_f32_e32 v65, v57, v197
	v_cvt_pk_bf16_f32 v64, v64, v65
	v_mul_f32_e32 v65, v57, v198
	v_mul_f32_e32 v66, v57, v199
	v_cvt_pk_bf16_f32 v65, v65, v66
	global_store_dwordx2 v[62:63], v[64:65], off offset:160
	v_mul_f32_e32 v64, v57, v78
	v_mul_f32_e32 v65, v57, v79
	v_cvt_pk_bf16_f32 v64, v64, v65
	v_mul_f32_e32 v65, v57, v80
	v_mul_f32_e32 v58, v57, v58
	v_mul_f32_e32 v59, v57, v59
	v_mul_f32_e32 v66, v57, v81
	v_cvt_pk_bf16_f32 v65, v65, v66
	global_store_dwordx2 v[62:63], v[64:65], off offset:192
	v_cvt_pk_bf16_f32 v58, v58, v59
	v_mul_f32_e32 v59, v57, v60
	v_mul_f32_e32 v57, v57, v61
	v_cvt_pk_bf16_f32 v59, v59, v57
	global_store_dwordx2 v[62:63], v[58:59], off offset:224
	s_mov_b64 s[0:1], exec
	v_readlane_b32 s10, v255, 17
	v_readlane_b32 s11, v255, 18
	s_and_b64 s[10:11], s[0:1], s[10:11]
	s_mov_b64 exec, s[10:11]
	s_cbranch_execz .LBB0_398
	v_log_f32_e32 v56, v56
	s_nop 0
	v_add_f32_e32 v58, v74, v56
	v_lshlrev_b64 v[56:57], 6, v[72:73]
	v_lshl_add_u64 v[56:57], s[12:13], 0, v[56:57]
	global_store_dword v[56:57], v58, off
.LBB0_398:
	s_or_b64 exec, exec, s[0:1]
	s_waitcnt lgkmcnt(0)
	s_barrier
	s_andn2_b64 vcc, exec, s[14:15]
	s_cbranch_vccnz .LBB0_321
	s_waitcnt vmcnt(19)
	v_and_b32_e32 v49, 0xffff0000, v24
	v_lshlrev_b32_e32 v48, 16, v24
	v_mul_f32_e32 v44, v49, v49
	v_and_b32_e32 v40, 0xffff0000, v25
	v_lshlrev_b32_e32 v41, 16, v25
	v_fmac_f32_e32 v44, v48, v48
	v_pk_mul_f32 v[42:43], v[40:41], v[40:41]
	s_mov_b32 s1, 0x800000
	v_add_f32_e32 v43, v43, v44
	v_add_f32_e32 v46, v42, v43
	v_and_b32_e32 v42, 0xffff0000, v26
	v_lshlrev_b32_e32 v43, 16, v26
	v_pk_mul_f32 v[44:45], v[42:43], v[42:43]
	s_add_i32 s0, s43, s38
	v_add_f32_e32 v45, v45, v46
	v_add_f32_e32 v50, v44, v45
	v_and_b32_e32 v44, 0xffff0000, v27
	v_lshlrev_b32_e32 v45, 16, v27
	v_pk_mul_f32 v[46:47], v[44:45], v[44:45]
	s_and_b32 s0, s0, 0x8000
	v_add_f32_e32 v47, v47, v50
	v_add_f32_e32 v46, v46, v47
	s_waitcnt vmcnt(18)
	v_and_b32_e32 v51, 0xffff0000, v28
	v_lshlrev_b32_e32 v50, 16, v28
	s_waitcnt vmcnt(8)
	v_mov_b32_e32 v53, v13
	v_mov_b32_e32 v54, v14
	s_waitcnt lgkmcnt(0)
	s_nop 1
	v_add_f32_dpp v46, v46, v46 quad_perm:[1,0,3,2] row_mask:0xf bank_mask:0xf
	v_mov_b32_e32 v55, v15
	s_waitcnt lgkmcnt(0)
	s_nop 1
	v_add_f32_dpp v46, v46, v46 quad_perm:[2,3,0,1] row_mask:0xf bank_mask:0xf
	s_waitcnt lgkmcnt(0)
	s_nop 1
	v_add_f32_dpp v46, v46, v46 row_half_mirror row_mask:0xf bank_mask:0xf
	s_waitcnt lgkmcnt(0)
	s_nop 1
	v_add_f32_dpp v46, v46, v46 row_ror:8 row_mask:0xf bank_mask:0xf
	v_fmamk_f32 v46, v46, 0x3c000000, v194
	v_cmp_gt_f32_e32 vcc, s1, v46
	v_mul_f32_e32 v47, 0x4b800000, v46
	s_nop 0
	v_cndmask_b32_e32 v46, v46, v47, vcc
	v_rsq_f32_e32 v46, v46
	s_nop 0
	v_mul_f32_e32 v47, 0x45800000, v46
	v_cndmask_b32_e32 v46, v46, v47, vcc
	v_mul_f32_e32 v47, v20, v46
	v_mul_f32_e32 v47, v47, v48
	v_mul_f32_e32 v48, v16, v46
	v_mul_f32_e32 v48, v48, v43
	v_mul_f32_e32 v43, v21, v46
	v_mul_f32_e32 v43, v43, v49
	v_mul_f32_e32 v49, v17, v46
	v_mul_f32_e32 v49, v49, v42
	v_mul_f32_e32 v42, v22, v46
	v_mul_f32_e32 v41, v42, v41
	v_mul_f32_e32 v42, v18, v46
	v_mul_f32_e32 v45, v42, v45
	v_mul_f32_e32 v42, v23, v46
	v_mul_f32_e32 v40, v42, v40
	v_mul_f32_e32 v42, v19, v46
	v_mul_f32_e32 v46, v42, v44
	v_cvt_pk_bf16_f32 v42, v47, v43
	v_cvt_pk_bf16_f32 v43, v41, v40
	v_add_u32_e32 v40, s0, v143
	v_add_u32_e32 v41, v146, v40
	v_cvt_pk_bf16_f32 v44, v48, v49
	v_cvt_pk_bf16_f32 v45, v45, v46
	ds_write_b128 v41, v[42:45]
	v_cvt_pk_f32_fp8_e32 v[42:43], v112
	v_cvt_pk_f32_fp8_sdwa v[44:45], v112 src0_sel:WORD_1
	v_cvt_pk_f32_fp8_e32 v[46:47], v113
	v_cvt_pk_bf16_f32 v42, v42, v43
	v_cvt_pk_bf16_f32 v43, v44, v45
	v_add_u32_e32 v40, v144, v40
	v_cvt_pk_f32_fp8_sdwa v[48:49], v113 src0_sel:WORD_1
	v_cvt_pk_bf16_f32 v44, v46, v47
	v_cvt_pk_bf16_f32 v45, v48, v49
	ds_write_b128 v40, v[42:45]
	v_mul_f32_e32 v46, v51, v51
	v_and_b32_e32 v42, 0xffff0000, v29
	v_lshlrev_b32_e32 v43, 16, v29
	v_fmac_f32_e32 v46, v50, v50
	v_pk_mul_f32 v[44:45], v[42:43], v[42:43]
	s_nop 0
	v_add_f32_e32 v45, v45, v46
	v_add_f32_e32 v48, v44, v45
	v_and_b32_e32 v44, 0xffff0000, v30
	v_lshlrev_b32_e32 v45, 16, v30
	v_pk_mul_f32 v[46:47], v[44:45], v[44:45]
	s_nop 0
	v_add_f32_e32 v47, v47, v48
	v_add_f32_e32 v52, v46, v47
	v_and_b32_e32 v46, 0xffff0000, v31
	v_lshlrev_b32_e32 v47, 16, v31
	v_pk_mul_f32 v[48:49], v[46:47], v[46:47]
	s_nop 0
	v_add_f32_e32 v49, v49, v52
	v_add_f32_e32 v48, v48, v49
	s_waitcnt lgkmcnt(0)
	s_nop 1
	v_add_f32_dpp v48, v48, v48 quad_perm:[1,0,3,2] row_mask:0xf bank_mask:0xf
	s_waitcnt lgkmcnt(0)
	s_nop 1
	v_add_f32_dpp v48, v48, v48 quad_perm:[2,3,0,1] row_mask:0xf bank_mask:0xf
	s_waitcnt lgkmcnt(0)
	s_nop 1
	v_add_f32_dpp v48, v48, v48 row_half_mirror row_mask:0xf bank_mask:0xf
	s_waitcnt lgkmcnt(0)
	s_nop 1
	v_add_f32_dpp v48, v48, v48 row_ror:8 row_mask:0xf bank_mask:0xf
	v_fmamk_f32 v48, v48, 0x3c000000, v194
	v_cmp_gt_f32_e32 vcc, s1, v48
	v_mul_f32_e32 v49, 0x4b800000, v48
	s_nop 0
	v_cndmask_b32_e32 v48, v48, v49, vcc
	v_rsq_f32_e32 v48, v48
	s_nop 0
	v_mul_f32_e32 v49, 0x45800000, v48
	v_cndmask_b32_e32 v48, v48, v49, vcc
	v_mul_f32_e32 v49, v20, v48
	v_mul_f32_e32 v49, v49, v50
	v_mul_f32_e32 v50, v16, v48
	v_mul_f32_e32 v45, v50, v45
	v_mul_f32_e32 v50, v21, v48
	v_mul_f32_e32 v50, v50, v51
	v_mul_f32_e32 v51, v17, v48
	v_mul_f32_e32 v44, v51, v44
	v_mul_f32_e32 v51, v22, v48
	v_mul_f32_e32 v43, v51, v43
	v_mul_f32_e32 v51, v18, v48
	v_mul_f32_e32 v47, v51, v47
	v_mul_f32_e32 v51, v23, v48
	v_mul_f32_e32 v51, v51, v42
	v_mul_f32_e32 v42, v19, v48
	v_mul_f32_e32 v46, v42, v46
	v_cvt_pk_bf16_f32 v42, v49, v50
	v_cvt_pk_bf16_f32 v43, v43, v51
	v_cvt_pk_bf16_f32 v44, v45, v44
	v_cvt_pk_bf16_f32 v45, v47, v46
	ds_write_b128 v41, v[42:45] offset:8192
	v_cvt_pk_f32_fp8_e32 v[42:43], v114
	v_cvt_pk_f32_fp8_sdwa v[44:45], v114 src0_sel:WORD_1
	v_cvt_pk_f32_fp8_e32 v[46:47], v115
	v_cvt_pk_bf16_f32 v42, v42, v43
	v_cvt_pk_bf16_f32 v43, v44, v45
	v_and_b32_e32 v51, 0xffff0000, v32
	v_cvt_pk_f32_fp8_sdwa v[48:49], v115 src0_sel:WORD_1
	v_cvt_pk_bf16_f32 v44, v46, v47
	v_cvt_pk_bf16_f32 v45, v48, v49
	ds_write_b128 v40, v[42:45] offset:8192
	v_lshlrev_b32_e32 v50, 16, v32
	v_mul_f32_e32 v46, v51, v51
	v_and_b32_e32 v42, 0xffff0000, v33
	v_lshlrev_b32_e32 v43, 16, v33
	v_fmac_f32_e32 v46, v50, v50
	v_pk_mul_f32 v[44:45], v[42:43], v[42:43]
	s_nop 0
	v_add_f32_e32 v45, v45, v46
	v_add_f32_e32 v48, v44, v45
	v_and_b32_e32 v44, 0xffff0000, v34
	v_lshlrev_b32_e32 v45, 16, v34
	v_pk_mul_f32 v[46:47], v[44:45], v[44:45]
	s_nop 0
	v_add_f32_e32 v47, v47, v48
	v_add_f32_e32 v52, v46, v47
	v_and_b32_e32 v46, 0xffff0000, v35
	v_lshlrev_b32_e32 v47, 16, v35
	v_pk_mul_f32 v[48:49], v[46:47], v[46:47]
	s_nop 0
	v_add_f32_e32 v49, v49, v52
	v_add_f32_e32 v48, v48, v49
	s_waitcnt lgkmcnt(0)
	s_nop 1
	v_add_f32_dpp v48, v48, v48 quad_perm:[1,0,3,2] row_mask:0xf bank_mask:0xf
	s_waitcnt lgkmcnt(0)
	s_nop 1
	v_add_f32_dpp v48, v48, v48 quad_perm:[2,3,0,1] row_mask:0xf bank_mask:0xf
	s_waitcnt lgkmcnt(0)
	s_nop 1
	v_add_f32_dpp v48, v48, v48 row_half_mirror row_mask:0xf bank_mask:0xf
	s_waitcnt lgkmcnt(0)
	s_nop 1
	v_add_f32_dpp v48, v48, v48 row_ror:8 row_mask:0xf bank_mask:0xf
	v_fmamk_f32 v48, v48, 0x3c000000, v194
	v_cmp_gt_f32_e32 vcc, s1, v48
	v_mul_f32_e32 v49, 0x4b800000, v48
	s_nop 0
	v_cndmask_b32_e32 v48, v48, v49, vcc
	v_rsq_f32_e32 v48, v48
	s_nop 0
	v_mul_f32_e32 v49, 0x45800000, v48
	v_cndmask_b32_e32 v48, v48, v49, vcc
	v_mul_f32_e32 v49, v20, v48
	v_mul_f32_e32 v49, v49, v50
	v_mul_f32_e32 v50, v16, v48
	v_mul_f32_e32 v45, v50, v45
	v_mul_f32_e32 v50, v21, v48
	v_mul_f32_e32 v50, v50, v51
	v_mul_f32_e32 v51, v17, v48
	v_mul_f32_e32 v44, v51, v44
	v_mul_f32_e32 v51, v22, v48
	v_mul_f32_e32 v43, v51, v43
	v_mul_f32_e32 v51, v18, v48
	v_mul_f32_e32 v47, v51, v47
	v_mul_f32_e32 v51, v23, v48
	v_mul_f32_e32 v51, v51, v42
	v_mul_f32_e32 v42, v19, v48
	v_mul_f32_e32 v46, v42, v46
	v_cvt_pk_bf16_f32 v42, v49, v50
	v_cvt_pk_bf16_f32 v43, v43, v51
	v_cvt_pk_bf16_f32 v44, v45, v44
	v_cvt_pk_bf16_f32 v45, v47, v46
	ds_write_b128 v41, v[42:45] offset:16384
	v_cvt_pk_f32_fp8_e32 v[42:43], v116
	v_cvt_pk_f32_fp8_sdwa v[44:45], v116 src0_sel:WORD_1
	v_cvt_pk_f32_fp8_e32 v[46:47], v117
	v_cvt_pk_bf16_f32 v42, v42, v43
	v_cvt_pk_bf16_f32 v43, v44, v45
	v_and_b32_e32 v51, 0xffff0000, v36
	v_cvt_pk_f32_fp8_sdwa v[48:49], v117 src0_sel:WORD_1
	v_cvt_pk_bf16_f32 v44, v46, v47
	v_cvt_pk_bf16_f32 v45, v48, v49
	ds_write_b128 v40, v[42:45] offset:16384
	v_lshlrev_b32_e32 v50, 16, v36
	v_mul_f32_e32 v46, v51, v51
	v_and_b32_e32 v42, 0xffff0000, v37
	v_lshlrev_b32_e32 v43, 16, v37
	v_fmac_f32_e32 v46, v50, v50
	v_pk_mul_f32 v[44:45], v[42:43], v[42:43]
	s_nop 0
	v_add_f32_e32 v45, v45, v46
	v_add_f32_e32 v48, v44, v45
	v_and_b32_e32 v44, 0xffff0000, v38
	v_lshlrev_b32_e32 v45, 16, v38
	v_pk_mul_f32 v[46:47], v[44:45], v[44:45]
	s_nop 0
	v_add_f32_e32 v47, v47, v48
	v_add_f32_e32 v52, v46, v47
	v_and_b32_e32 v46, 0xffff0000, v39
	v_lshlrev_b32_e32 v47, 16, v39
	v_pk_mul_f32 v[48:49], v[46:47], v[46:47]
	s_nop 0
	v_add_f32_e32 v49, v49, v52
	v_add_f32_e32 v48, v48, v49
	v_mov_b32_e32 v52, v12
	s_waitcnt lgkmcnt(0)
	s_nop 1
	v_add_f32_dpp v48, v48, v48 quad_perm:[1,0,3,2] row_mask:0xf bank_mask:0xf
	s_waitcnt lgkmcnt(0)
	s_nop 1
	v_add_f32_dpp v48, v48, v48 quad_perm:[2,3,0,1] row_mask:0xf bank_mask:0xf
	s_waitcnt lgkmcnt(0)
	s_nop 1
	v_add_f32_dpp v48, v48, v48 row_half_mirror row_mask:0xf bank_mask:0xf
	s_waitcnt lgkmcnt(0)
	s_nop 1
	v_add_f32_dpp v48, v48, v48 row_ror:8 row_mask:0xf bank_mask:0xf
	v_fmamk_f32 v48, v48, 0x3c000000, v194
	v_cmp_gt_f32_e32 vcc, s1, v48
	v_mul_f32_e32 v49, 0x4b800000, v48
	s_nop 0
	v_cndmask_b32_e32 v48, v48, v49, vcc
	v_rsq_f32_e32 v48, v48
	s_nop 0
	v_mul_f32_e32 v49, 0x45800000, v48
	v_cndmask_b32_e32 v48, v48, v49, vcc
	v_mul_f32_e32 v49, v20, v48
	v_mul_f32_e32 v49, v49, v50
	v_mul_f32_e32 v50, v16, v48
	v_mul_f32_e32 v45, v50, v45
	v_mul_f32_e32 v50, v21, v48
	v_mul_f32_e32 v50, v50, v51
	v_mul_f32_e32 v51, v17, v48
	v_mul_f32_e32 v44, v51, v44
	v_mul_f32_e32 v51, v22, v48
	v_mul_f32_e32 v43, v51, v43
	v_mul_f32_e32 v51, v18, v48
	v_mul_f32_e32 v47, v51, v47
	v_mul_f32_e32 v51, v23, v48
	v_mul_f32_e32 v51, v51, v42
	v_mul_f32_e32 v42, v19, v48
	v_mul_f32_e32 v46, v42, v46
	v_cvt_pk_bf16_f32 v42, v49, v50
	v_cvt_pk_bf16_f32 v43, v43, v51
	v_cvt_pk_bf16_f32 v44, v45, v44
	v_cvt_pk_bf16_f32 v45, v47, v46
	ds_write_b128 v41, v[42:45] offset:24576
	v_cvt_pk_f32_fp8_e32 v[42:43], v118
	v_cvt_pk_f32_fp8_sdwa v[44:45], v118 src0_sel:WORD_1
	v_cvt_pk_f32_fp8_e32 v[46:47], v119
	v_cvt_pk_f32_fp8_sdwa v[48:49], v119 src0_sel:WORD_1
	v_cvt_pk_bf16_f32 v42, v42, v43
	v_cvt_pk_bf16_f32 v43, v44, v45
	v_cvt_pk_bf16_f32 v44, v46, v47
	v_cvt_pk_bf16_f32 v45, v48, v49
	ds_write_b128 v40, v[42:45] offset:24576
	v_mov_b32_e32 v40, v0
	v_mov_b32_e32 v41, v1
	v_mov_b32_e32 v42, v2
	v_mov_b32_e32 v43, v3
	v_mov_b32_e32 v44, v4
	v_mov_b32_e32 v45, v5
	v_mov_b32_e32 v46, v6
	v_mov_b32_e32 v47, v7
	v_mov_b32_e32 v48, v8
	v_mov_b32_e32 v49, v9
	v_mov_b32_e32 v50, v10
	v_mov_b32_e32 v51, v11
	s_branch .LBB0_321
